# v058 + the early layer-1 conversion and the shortened tail are taken only when gridDim.x == 256 (generic path kept otherwise)
# speedup vs baseline: 1.0391x; 1.0032x over previous
; #define LAS __attribute__((address_space(3)))
; __device__ __forceinline__ void tr_item(const float* W, int N, bf16* WT, int dpitch, int koff, int drow0, int k0, int n0, LAS float* scr, int lane) {
;     float tv[32];
; #pragma unroll
;     for (int i = 0; i < 32; ++i) tv[i] = W[(size_t)(k0 + 2 * i + (lane >> 5)) * N + n0 + (lane & 31)];
; __global__ void __launch_bounds__(512, 2) fwd_mega(Args a) {
;     ...
;     auto convert_items = [&](int LL, int lo, int hi, int w0, int nw_, size_t wd_off) __attribute__((always_inline)) {
;         LAS float* scr = (LAS float*)(lds + wave * 16384);
;         for (int it0 = lo + w0; it0 < hi; it0 += nw_) {
;             int it = it0;
;             if (it < 2688) { const int kb = it / 168, nb = it % 168; tr_item(INF(6) + (size_t)LL * D * INC, INC, WSP(WS_WIN), 1024, 0, 32 * nb, 64 * kb, 32 * nb, scr, lane); continue; } it -= 2688;
;             if (it < 512) { const int kb = it / 32, nb = it % 32; tr_item(INF(13) + (size_t)LL * D * D, D, WSP(WS_PAB), 1024, 0, 32 * nb, 64 * kb, 32 * nb, scr, lane); continue; } it -= 512;
;             if (it < 512) { const int kb = it / 32, nb = it % 32; tr_item(INF(12) + (size_t)LL * D * D, D, WSP(WS_PAB), 1024, 0, 1024 + 32 * nb, 64 * kb, 32 * nb, scr, lane); continue; } it -= 512;
;             if (it < 512) { const int kb = it / 32, nb = it % 32; tr_item(INF(14) + (size_t)LL * D * D, D, WSP(WS_WO2), 1024, 0, 32 * nb, 64 * kb, 32 * nb, scr, lane); continue; } it -= 512;
;             if (it < 1408) { const int kb = it / 88, nb = it % 88, n0 = 32 * nb; tr_item(INF(16) + (size_t)LL * D * FF, FF, WSP(WS_WGU), 1024, 0, (n0 >> 7) * 256 + (n0 & 127), 64 * kb, n0, scr, lane); continue; } it -= 1408;
;             if (it < 1408) { const int kb = it / 88, nb = it % 88, n0 = 32 * nb; tr_item(INF(17) + (size_t)LL * D * FF, FF, WSP(WS_WGU), 1024, 0, (n0 >> 7) * 256 + 128 + (n0 & 127), 64 * kb, n0, scr, lane); continue; } it -= 1408;
;             { const int kb = it / 32, nb = it % 32; tr_item(INF(20) + (size_t)LL * FF * D, D, WSP(wd_off), 2816, 0, 32 * nb, 64 * kb, 32 * nb, scr, lane); }
.LBB0_850:
	s_cmpk_lg_u32 s3, 0x100
	s_cbranch_scc1 .Lgc_skip
	s_cmpk_lt_u32 s2, 0x80
	s_cbranch_scc1 .Lgc_skip
	v_writelane_b32 v250, s0, 0
	v_writelane_b32 v250, s1, 1
	v_writelane_b32 v250, s2, 2
	v_writelane_b32 v250, s3, 3
	v_writelane_b32 v250, s4, 4
	v_writelane_b32 v250, s5, 5
	v_writelane_b32 v250, s6, 6
	v_writelane_b32 v250, s7, 7
	v_writelane_b32 v250, s8, 8
	v_writelane_b32 v250, s9, 9
	v_writelane_b32 v250, s10, 10
	v_writelane_b32 v250, s11, 11
	v_writelane_b32 v250, s12, 12
	v_writelane_b32 v250, s13, 13
	v_writelane_b32 v250, s14, 14
	v_writelane_b32 v250, s15, 15
	v_writelane_b32 v250, s16, 16
	v_writelane_b32 v250, s17, 17
	v_writelane_b32 v250, s18, 18
	v_writelane_b32 v250, s19, 19
	v_writelane_b32 v250, s20, 20
	v_writelane_b32 v250, s21, 21
	v_writelane_b32 v250, s22, 22
	v_writelane_b32 v250, s23, 23
	v_writelane_b32 v250, s24, 24
	v_writelane_b32 v250, s25, 25
	v_writelane_b32 v250, s26, 26
	v_writelane_b32 v250, s27, 27
	v_writelane_b32 v250, s28, 28
	v_writelane_b32 v250, s29, 29
	v_writelane_b32 v250, s30, 30
	v_writelane_b32 v250, s31, 31
	v_writelane_b32 v250, s32, 32
	v_writelane_b32 v250, s33, 33
	v_writelane_b32 v250, s34, 34
	v_writelane_b32 v250, s35, 35
	v_writelane_b32 v250, s36, 36
	v_writelane_b32 v250, s37, 37
	v_writelane_b32 v250, s38, 38
	v_writelane_b32 v250, s39, 39
	v_writelane_b32 v250, s40, 40
	v_writelane_b32 v250, s41, 41
	v_writelane_b32 v250, s42, 42
	v_writelane_b32 v250, s43, 43
	v_writelane_b32 v250, s44, 44
	v_writelane_b32 v250, s45, 45
	v_writelane_b32 v250, s46, 46
	v_writelane_b32 v250, s47, 47
	v_writelane_b32 v250, s48, 48
	v_writelane_b32 v250, s49, 49
	v_writelane_b32 v250, s50, 50
	v_writelane_b32 v250, s51, 51
	v_writelane_b32 v250, s52, 52
	v_writelane_b32 v250, s53, 53
	v_writelane_b32 v250, s54, 54
	v_writelane_b32 v250, s55, 55
	v_writelane_b32 v250, s56, 56
	v_writelane_b32 v250, s57, 57
	v_writelane_b32 v250, s58, 58
	v_writelane_b32 v250, s59, 59
	v_writelane_b32 v250, s60, 60
	v_writelane_b32 v250, s61, 61
	v_writelane_b32 v250, s62, 62
	v_writelane_b32 v250, s63, 63
	v_writelane_b32 v251, s64, 0
	v_writelane_b32 v251, s65, 1
	v_writelane_b32 v251, s66, 2
	v_writelane_b32 v251, s67, 3
	v_writelane_b32 v251, s68, 4
	v_writelane_b32 v251, s69, 5
	v_writelane_b32 v251, s70, 6
	v_writelane_b32 v251, s71, 7
	v_writelane_b32 v251, s72, 8
	v_writelane_b32 v251, s73, 9
	v_writelane_b32 v251, s74, 10
	v_writelane_b32 v251, s75, 11
	v_writelane_b32 v251, s76, 12
	v_writelane_b32 v251, s77, 13
	v_writelane_b32 v251, s78, 14
	v_writelane_b32 v251, s79, 15
	v_writelane_b32 v251, s80, 16
	v_writelane_b32 v251, s81, 17
	v_writelane_b32 v251, s82, 18
	v_writelane_b32 v251, s83, 19
	v_writelane_b32 v251, s84, 20
	v_writelane_b32 v251, s85, 21
	v_writelane_b32 v251, s86, 22
	v_writelane_b32 v251, s87, 23
	v_writelane_b32 v251, s88, 24
	v_writelane_b32 v251, s89, 25
	v_writelane_b32 v251, s90, 26
	v_writelane_b32 v251, s91, 27
	v_writelane_b32 v251, s92, 28
	v_writelane_b32 v251, s93, 29
	v_writelane_b32 v251, s94, 30
	v_writelane_b32 v251, s95, 31
	v_writelane_b32 v251, s96, 32
	v_writelane_b32 v251, s97, 33
	v_writelane_b32 v251, vcc_lo, 34
	v_writelane_b32 v251, vcc_hi, 35
	v_readlane_b32 s4, v247, 40
	v_readlane_b32 s5, v247, 41
	s_nop 4
	s_mov_b64 s[6:7], s[26:27]
	v_lshlrev_b32_e32 v2, 2, v205
	v_mul_u32_u24_e32 v6, 0x84, v200
	v_readlane_b32 s10, v246, 3
	v_mov_b32_e32 v3, 0
	v_mov_b32_e32 v7, v3
	v_add3_u32 v28, s10, v2, v6
	v_and_b32_e32 v6, 56, v204
	v_mul_u32_u24_e32 v8, 0x84, v6
	v_lshlrev_b32_e32 v6, 1, v6
	s_waitcnt lgkmcnt(0)
	v_lshl_add_u64 v[4:5], s[4:5], 0, v[2:3]
	v_lshl_add_u64 v[26:27], s[6:7], 0, v[6:7]
	s_mov_b64 s[4:5], 0xf600000
	v_lshl_add_u64 v[6:7], v[26:27], 0, s[4:5]
	v_readlane_b32 s4, v247, 32
	v_readlane_b32 s5, v247, 33
	v_readlane_b32 s6, v247, 34
	v_readlane_b32 s7, v247, 35
	s_nop 4
	v_lshlrev_b32_e32 v9, 2, v201
	s_mov_b64 s[8:9], 0xb00000
	v_add3_u32 v29, s10, v8, v9
	v_readlane_b32 s10, v247, 28
	v_readlane_b32 s11, v247, 29
	s_nop 4
	s_waitcnt lgkmcnt(0)
	v_lshl_add_u64 v[8:9], s[6:7], 0, v[2:3]
	s_mov_b64 s[6:7], 0x1a80000
	v_lshl_add_u64 v[12:13], s[4:5], 0, v[2:3]
	v_lshl_add_u64 v[4:5], v[4:5], 0, s[8:9]
	v_lshl_add_u64 v[8:9], v[8:9], 0, s[8:9]
	v_lshl_add_u64 v[10:11], v[26:27], 0, s[6:7]
	v_lshl_add_u64 v[12:13], v[12:13], 0, s[8:9]
	v_readlane_b32 s8, v247, 12
	v_readlane_b32 s9, v247, 13
	v_readlane_b32 s4, v247, 24
	v_readlane_b32 s5, v247, 25
	v_readlane_b32 s6, v247, 26
	v_readlane_b32 s7, v247, 27
	s_nop 4
	v_lshl_add_u64 v[14:15], s[10:11], 0, v[2:3]
	s_mov_b64 s[10:11], 0x400000
	s_mov_b64 s[12:13], 0x1680000
	s_waitcnt vmcnt(3) lgkmcnt(0)
	v_lshl_add_u64 v[24:25], s[8:9], 0, v[2:3]
	s_waitcnt vmcnt(1)
	v_lshl_add_u64 v[18:19], s[4:5], 0, v[2:3]
	s_mov_b64 s[4:5], 0x1280000
	v_lshl_add_u64 v[20:21], v[26:27], 0, s[4:5]
	s_mov_b64 s[4:5], 0x1500000
	v_lshl_add_u64 v[22:23], s[6:7], 0, v[2:3]
	v_lshl_add_u64 v[24:25], v[24:25], 0, s[4:5]
	s_mov_b64 s[4:5], 0x800000
	v_or_b32_e32 v30, 8, v201
	v_or_b32_e32 v31, 16, v201
	v_or_b32_e32 v32, 24, v201
	v_lshl_add_u64 v[14:15], v[14:15], 0, s[10:11]
	v_lshl_add_u64 v[16:17], v[26:27], 0, s[12:13]
	v_lshl_add_u64 v[18:19], v[18:19], 0, s[10:11]
	v_lshl_add_u64 v[22:23], v[22:23], 0, s[10:11]
	v_lshl_add_u64 v[26:27], v[26:27], 0, s[4:5]
	s_lshl_b32 s4, s22, 5
	s_lshl_b32 s5, s77, 5
	s_lshl_b32 s12, s22, 1
	s_lshl_b32 s13, s77, 1
	s_mov_b32 s7, 0
	s_movk_i32 s14, 0x7fff
	s_mov_b32 s15, 0xffff0000
	s_movk_i32 s16, 0x5000
	s_mov_b32 s17, 0xb000
	s_mov_b32 s18, 0x10000
	s_mov_b32 s19, 0x16000
	s_mov_b32 s20, 0x1b000
	s_mov_b32 s21, 0x21000
	s_mov_b32 s23, 0x26000
	s_mov_b32 s24, 0x2c000
	s_mov_b32 s25, 0x31000
	s_mov_b32 s28, 0x37000
	s_mov_b32 s29, 0x3c000
	s_mov_b32 s30, 0x42000
	s_mov_b32 s31, 0x47000
	s_mov_b32 s34, 0x4d000
	s_mov_b32 s35, 0x52000
	s_mov_b32 s36, 0x58000
	s_mov_b32 s37, 0x5d000
	s_mov_b32 s38, 0x63000
	s_mov_b32 s39, 0x68000
	s_mov_b32 s40, 0x6e000
	s_mov_b32 s41, 0x73000
	s_mov_b32 s42, 0x79000
	s_mov_b32 s43, 0x7e000
	s_mov_b32 s44, 0x84000
	s_mov_b32 s45, 0x89000
	s_mov_b32 s46, 0x8f000
	s_mov_b32 s47, 0x94000
	s_mov_b32 s48, 0x9a000
	s_mov_b32 s49, 0x9f000
	s_mov_b32 s50, 0xa5000
	s_mov_b32 s51, 0xaa000
	s_movk_i32 s52, 0x5400
	v_add_u32_e32 v33, 0x400, v28
	v_add_u32_e32 v34, 0x800, v28
	v_add_u32_e32 v35, 0xc00, v28
	v_add_u32_e32 v36, 0x1000, v28
	v_add_u32_e32 v37, 0x1400, v28
	v_add_u32_e32 v38, 0x1800, v28
	v_add_u32_e32 v39, 0x1c00, v28
	s_sub_i32 s53, s22, 0x400
	s_lshl_b32 s4, s53, 5
	s_lshl_b32 s12, s53, 1
	s_branch .Lgc_986

; #define LAS __attribute__((address_space(3)))
; __global__ void __launch_bounds__(512, 2) fwd_mega(Args a) {
;     ...
;     auto convert_items = [&](int LL, int lo, int hi, int w0, int nw_, size_t wd_off) __attribute__((always_inline)) {
;         LAS float* scr = (LAS float*)(lds + wave * 16384);
;         for (int it0 = lo + w0; it0 < hi; it0 += nw_) {
;             int it = it0;
;             if (it < 2688) { const int kb = it / 168, nb = it % 168; tr_item(INF(6) + (size_t)LL * D * INC, INC, WSP(WS_WIN), 1024, 0, 32 * nb, 64 * kb, 32 * nb, scr, lane); continue; } it -= 2688;
;     ...
;         if constexpr (l + 1 < NL) {
;             __syncthreads();
;             convert_items(l + 1, 0, 8448, gw, NGW, WS_WD1);
;             for (int it = gw; it < 160; it += NGW) sgu_wfrag_item(INF(10) + (size_t)(l + 1) * 8 * 128 * 128, (v4u*)(a.ws + WS_WF), it, lane);
.LBB0_983:
	v_readlane_b32 s4, v246, 4
	v_readlane_b32 s5, v246, 5
	s_andn2_b64 vcc, exec, s[4:5]
	s_barrier
	s_cbranch_vccnz .LBB0_1010
	v_readlane_b32 s4, v247, 40
	v_readlane_b32 s5, v247, 41
	s_nop 4
	s_mov_b64 s[6:7], s[26:27]
	v_lshlrev_b32_e32 v2, 2, v205
	v_mul_u32_u24_e32 v6, 0x84, v200
	v_readlane_b32 s10, v246, 3
	v_mov_b32_e32 v3, 0
	v_mov_b32_e32 v7, v3
	v_add3_u32 v28, s10, v2, v6
	v_and_b32_e32 v6, 56, v204
	v_mul_u32_u24_e32 v8, 0x84, v6
	v_lshlrev_b32_e32 v6, 1, v6
	s_waitcnt lgkmcnt(0)
	v_lshl_add_u64 v[4:5], s[4:5], 0, v[2:3]
	v_lshl_add_u64 v[26:27], s[6:7], 0, v[6:7]
	s_mov_b64 s[4:5], 0xf600000
	v_lshl_add_u64 v[6:7], v[26:27], 0, s[4:5]
	v_readlane_b32 s4, v247, 32
	v_readlane_b32 s5, v247, 33
	v_readlane_b32 s6, v247, 34
	v_readlane_b32 s7, v247, 35
	s_nop 4
	v_lshlrev_b32_e32 v9, 2, v201
	s_mov_b64 s[8:9], 0xb00000
	v_add3_u32 v29, s10, v8, v9
	v_readlane_b32 s10, v247, 28
	v_readlane_b32 s11, v247, 29
	s_nop 4
	s_waitcnt lgkmcnt(0)
	v_lshl_add_u64 v[8:9], s[6:7], 0, v[2:3]
	s_mov_b64 s[6:7], 0x1a80000
	v_lshl_add_u64 v[12:13], s[4:5], 0, v[2:3]
	v_lshl_add_u64 v[4:5], v[4:5], 0, s[8:9]
	v_lshl_add_u64 v[8:9], v[8:9], 0, s[8:9]
	v_lshl_add_u64 v[10:11], v[26:27], 0, s[6:7]
	v_lshl_add_u64 v[12:13], v[12:13], 0, s[8:9]
	v_readlane_b32 s8, v247, 12
	v_readlane_b32 s9, v247, 13
	v_readlane_b32 s4, v247, 24
	v_readlane_b32 s5, v247, 25
	v_readlane_b32 s6, v247, 26
	v_readlane_b32 s7, v247, 27
	s_nop 4
	v_lshl_add_u64 v[14:15], s[10:11], 0, v[2:3]
	s_mov_b64 s[10:11], 0x400000
	s_mov_b64 s[12:13], 0x1680000
	s_waitcnt vmcnt(3) lgkmcnt(0)
	v_lshl_add_u64 v[24:25], s[8:9], 0, v[2:3]
	s_waitcnt vmcnt(1)
	v_lshl_add_u64 v[18:19], s[4:5], 0, v[2:3]
	s_mov_b64 s[4:5], 0x1280000
	v_lshl_add_u64 v[20:21], v[26:27], 0, s[4:5]
	s_mov_b64 s[4:5], 0x1500000
	v_lshl_add_u64 v[22:23], s[6:7], 0, v[2:3]
	v_lshl_add_u64 v[24:25], v[24:25], 0, s[4:5]
	s_mov_b64 s[4:5], 0x800000
	v_or_b32_e32 v30, 8, v201
	v_or_b32_e32 v31, 16, v201
	v_or_b32_e32 v32, 24, v201
	v_lshl_add_u64 v[14:15], v[14:15], 0, s[10:11]
	v_lshl_add_u64 v[16:17], v[26:27], 0, s[12:13]
	v_lshl_add_u64 v[18:19], v[18:19], 0, s[10:11]
	v_lshl_add_u64 v[22:23], v[22:23], 0, s[10:11]
	v_lshl_add_u64 v[26:27], v[26:27], 0, s[4:5]
	s_lshl_b32 s4, s22, 5
	s_lshl_b32 s5, s77, 5
	s_lshl_b32 s12, s22, 1
	s_lshl_b32 s13, s77, 1
	s_mov_b32 s7, 0
	s_movk_i32 s14, 0x7fff
	s_mov_b32 s15, 0xffff0000
	s_movk_i32 s16, 0x5000
	s_mov_b32 s17, 0xb000
	s_mov_b32 s18, 0x10000
	s_mov_b32 s19, 0x16000
	s_mov_b32 s20, 0x1b000
	s_mov_b32 s21, 0x21000
	s_mov_b32 s23, 0x26000
	s_mov_b32 s24, 0x2c000
	s_mov_b32 s25, 0x31000
	s_mov_b32 s28, 0x37000
	s_mov_b32 s29, 0x3c000
	s_mov_b32 s30, 0x42000
	s_mov_b32 s31, 0x47000
	s_mov_b32 s34, 0x4d000
	s_mov_b32 s35, 0x52000
	s_mov_b32 s36, 0x58000
	s_mov_b32 s37, 0x5d000
	s_mov_b32 s38, 0x63000
	s_mov_b32 s39, 0x68000
	s_mov_b32 s40, 0x6e000
	s_mov_b32 s41, 0x73000
	s_mov_b32 s42, 0x79000
	s_mov_b32 s43, 0x7e000
	s_mov_b32 s44, 0x84000
	s_mov_b32 s45, 0x89000
	s_mov_b32 s46, 0x8f000
	s_mov_b32 s47, 0x94000
	s_mov_b32 s48, 0x9a000
	s_mov_b32 s49, 0x9f000
	s_mov_b32 s50, 0xa5000
	s_mov_b32 s51, 0xaa000
	s_movk_i32 s52, 0x5400
	v_add_u32_e32 v33, 0x400, v28
	v_add_u32_e32 v34, 0x800, v28
	v_add_u32_e32 v35, 0xc00, v28
	v_add_u32_e32 v36, 0x1000, v28
	v_add_u32_e32 v37, 0x1400, v28
	v_add_u32_e32 v38, 0x1800, v28
	v_add_u32_e32 v39, 0x1c00, v28
	s_mov_b32 s53, s22
	s_cmpk_lg_u32 s3, 0x100
	s_cbranch_scc1 .Lgc_tail0
	s_addk_i32 s53, 0x1080
	s_add_i32 s4, s4, 0x21000
	s_addk_i32 s12, 0x2100
.Lgc_tail0:
	s_branch .LBB0_986
